# attention step: next-tile K fragment reads moved from the exp segment into the light gaps of the first PV MFMAs
# baseline (speedup 1.0000x reference)
.Lat_nomask_526:
	v_add_u32_e32 v3, s58, v244
	ds_read_b64_tr_b16 v[200:201], v250 offset:8192
	ds_read_b64_tr_b16 v[202:203], v250 offset:8704
	ds_read_b64_tr_b16 v[204:205], v250 offset:12288
	ds_read_b64_tr_b16 v[206:207], v250 offset:12800
	s_waitcnt lgkmcnt(4)
	v_mfma_f32_32x32x16_bf16 v[32:47], v[176:179], v[192:195], v[32:47]
	v_max3_f32 v2, v128, v129, v144
	v_max3_f32 v4, v130, v131, v145
	v_max3_f32 v2, v2, v146, v147
	ds_read_b128 v[208:211], v3
	ds_read_b128 v[212:215], v3 offset:512
	v_mfma_f32_32x32x16_bf16 v[48:63], v[176:179], v[196:199], v[48:63]
	v_max3_f32 v2, v2, v132, v133
	v_max3_f32 v4, v4, v134, v135
	v_max3_f32 v2, v2, v148, v149
	ds_read_b128 v[216:219], v3 offset:2048
	ds_read_b128 v[220:223], v3 offset:2560
	ds_read_b64_tr_b16 v[192:193], v250 offset:1024
	ds_read_b64_tr_b16 v[194:195], v250 offset:1536
	ds_read_b64_tr_b16 v[196:197], v250 offset:5120
	ds_read_b64_tr_b16 v[198:199], v250 offset:5632
	s_waitcnt lgkmcnt(8)
	v_mfma_f32_32x32x16_bf16 v[64:79], v[176:179], v[200:203], v[64:79]
	v_max3_f32 v4, v4, v150, v151
	v_max3_f32 v2, v2, v136, v137
	v_max3_f32 v4, v4, v138, v139
	ds_read_b128 v[224:227], v3 offset:4096
	v_mfma_f32_32x32x16_bf16 v[80:95], v[176:179], v[204:207], v[80:95]
	v_max3_f32 v2, v2, v152, v153
	v_max3_f32 v4, v4, v154, v155
	v_max3_f32 v2, v2, v140, v141
	ds_read_b128 v[228:231], v3 offset:4608
	ds_read_b64_tr_b16 v[200:201], v250 offset:9216
	ds_read_b64_tr_b16 v[202:203], v250 offset:9728
	ds_read_b64_tr_b16 v[204:205], v250 offset:13312
	ds_read_b64_tr_b16 v[206:207], v250 offset:13824
	s_waitcnt lgkmcnt(6)
	v_mfma_f32_32x32x16_bf16 v[32:47], v[180:183], v[192:195], v[32:47]
	v_max3_f32 v4, v4, v142, v143
	v_max3_f32 v2, v2, v156, v157
	v_max3_f32 v4, v4, v158, v159
	ds_read_b128 v[232:235], v3 offset:6144
	v_mfma_f32_32x32x16_bf16 v[48:63], v[180:183], v[196:199], v[48:63]
	v_max_f32_e32 v2, v2, v4
	v_mov_b32_e32 v4, v2
	s_nop 1
	v_permlane32_swap_b32_e32 v2, v4
	v_max_f32_e32 v2, v2, v4
	ds_read_b128 v[240:243], v3 offset:6656
	v_mov_b32_e32 v5, 0x41400000
	v_cmp_gt_f32_e32 vcc, v2, v5
	s_mov_b64 s[68:69], vcc
	s_cmp_lg_u64 vcc, 0
	s_cbranch_scc0 .Lat_noresc_443
	v_max_f32_e32 v4, 0, v2
	v_add_f32_e32 v248, v248, v4
	v_sub_f32_e32 v128, v128, v4
	v_sub_f32_e32 v129, v129, v4
	v_sub_f32_e32 v130, v130, v4
	v_sub_f32_e32 v131, v131, v4
	v_sub_f32_e32 v132, v132, v4
	v_sub_f32_e32 v133, v133, v4
	v_sub_f32_e32 v134, v134, v4
	v_sub_f32_e32 v135, v135, v4
	v_sub_f32_e32 v136, v136, v4
	v_sub_f32_e32 v137, v137, v4
	v_sub_f32_e32 v138, v138, v4
	v_sub_f32_e32 v139, v139, v4
	v_sub_f32_e32 v140, v140, v4
	v_sub_f32_e32 v141, v141, v4
	v_sub_f32_e32 v142, v142, v4
	v_sub_f32_e32 v143, v143, v4
	v_sub_f32_e32 v144, v144, v4
	v_sub_f32_e32 v145, v145, v4
	v_sub_f32_e32 v146, v146, v4
	v_sub_f32_e32 v147, v147, v4
	v_sub_f32_e32 v148, v148, v4
	v_sub_f32_e32 v149, v149, v4
	v_sub_f32_e32 v150, v150, v4
	v_sub_f32_e32 v151, v151, v4
	v_sub_f32_e32 v152, v152, v4
	v_sub_f32_e32 v153, v153, v4
	v_sub_f32_e32 v154, v154, v4
	v_sub_f32_e32 v155, v155, v4
	v_sub_f32_e32 v156, v156, v4
	v_sub_f32_e32 v157, v157, v4
	v_sub_f32_e32 v158, v158, v4
	v_sub_f32_e32 v159, v159, v4
	v_xor_b32_e32 v5, 0x80000000, v248
	v_mov_b32_e32 v160, v5
	v_mov_b32_e32 v161, v5
	v_mov_b32_e32 v162, v5
	v_mov_b32_e32 v163, v5
	v_mov_b32_e32 v164, v5
	v_mov_b32_e32 v165, v5
	v_mov_b32_e32 v166, v5
	v_mov_b32_e32 v167, v5
	v_mov_b32_e32 v168, v5
	v_mov_b32_e32 v169, v5
	v_mov_b32_e32 v170, v5
	v_mov_b32_e32 v171, v5
	v_mov_b32_e32 v172, v5
	v_mov_b32_e32 v173, v5
	v_mov_b32_e32 v174, v5
	v_mov_b32_e32 v175, v5
	v_xor_b32_e32 v6, 0x80000000, v4
	v_exp_f32_e32 v6, v6
	s_nop 0
	v_mul_f32_e32 v247, v247, v6
	v_and_b32_e32 v7, 31, v237
	v_lshl_add_u32 v7, v7, 2, v249
	v_cmp_eq_u32_e32 vcc, 0, v252
	s_and_saveexec_b64 s[60:61], vcc
	ds_write_b32 v7, v6
	s_or_b64 exec, exec, s[60:61]
.Lat_noresc_443:
	ds_read_b64_tr_b16 v[192:193], v250 offset:2048
	ds_read_b64_tr_b16 v[194:195], v250 offset:2560
	ds_read_b64_tr_b16 v[196:197], v250 offset:6144
	ds_read_b64_tr_b16 v[198:199], v250 offset:6656
	s_waitcnt lgkmcnt(6)
	v_mfma_f32_32x32x16_bf16 v[64:79], v[180:183], v[200:203], v[64:79]
	v_exp_f32_e32 v128, v128
	v_exp_f32_e32 v129, v129
	v_exp_f32_e32 v130, v130
	v_mfma_f32_32x32x16_bf16 v[80:95], v[180:183], v[204:207], v[80:95]
	v_exp_f32_e32 v131, v131
	v_exp_f32_e32 v132, v132
	v_exp_f32_e32 v133, v133
	ds_read_b64_tr_b16 v[200:201], v250 offset:10240
	ds_read_b64_tr_b16 v[202:203], v250 offset:10752
	ds_read_b64_tr_b16 v[204:205], v250 offset:14336
	ds_read_b64_tr_b16 v[206:207], v250 offset:14848
	s_waitcnt lgkmcnt(4)
	v_mfma_f32_32x32x16_bf16 v[32:47], v[184:187], v[192:195], v[32:47]
	v_exp_f32_e32 v134, v134
	v_exp_f32_e32 v135, v135
	v_exp_f32_e32 v136, v136
	v_mfma_f32_32x32x16_bf16 v[48:63], v[184:187], v[196:199], v[48:63]
	v_exp_f32_e32 v137, v137
	v_exp_f32_e32 v138, v138
	v_exp_f32_e32 v139, v139
	ds_read_b64_tr_b16 v[192:193], v250 offset:3072
	ds_read_b64_tr_b16 v[194:195], v250 offset:3584
	ds_read_b64_tr_b16 v[196:197], v250 offset:7168
	ds_read_b64_tr_b16 v[198:199], v250 offset:7680
	s_waitcnt lgkmcnt(4)
	v_mfma_f32_32x32x16_bf16 v[64:79], v[184:187], v[200:203], v[64:79]
	v_exp_f32_e32 v140, v140
	v_exp_f32_e32 v141, v141
	v_exp_f32_e32 v142, v142
	v_mfma_f32_32x32x16_bf16 v[80:95], v[184:187], v[204:207], v[80:95]
	v_exp_f32_e32 v143, v143
	v_exp_f32_e32 v144, v144
	v_exp_f32_e32 v145, v145
	ds_read_b64_tr_b16 v[200:201], v250 offset:11264
	ds_read_b64_tr_b16 v[202:203], v250 offset:11776
	ds_read_b64_tr_b16 v[204:205], v250 offset:15360
	ds_read_b64_tr_b16 v[206:207], v250 offset:15872
	s_waitcnt lgkmcnt(4)
	v_mfma_f32_32x32x16_bf16 v[32:47], v[188:191], v[192:195], v[32:47]
	v_exp_f32_e32 v146, v146
	v_exp_f32_e32 v147, v147
	v_exp_f32_e32 v148, v148
	v_mfma_f32_32x32x16_bf16 v[48:63], v[188:191], v[196:199], v[48:63]
	v_exp_f32_e32 v149, v149
	v_exp_f32_e32 v150, v150
	v_exp_f32_e32 v151, v151
	s_waitcnt lgkmcnt(0)
	v_mfma_f32_32x32x16_bf16 v[64:79], v[188:191], v[200:203], v[64:79]
	v_exp_f32_e32 v152, v152
	v_exp_f32_e32 v153, v153
	v_exp_f32_e32 v154, v154
	v_exp_f32_e32 v155, v155
	v_mfma_f32_32x32x16_bf16 v[80:95], v[188:191], v[204:207], v[80:95]
	v_exp_f32_e32 v156, v156
	v_exp_f32_e32 v157, v157
	v_exp_f32_e32 v158, v158
	v_exp_f32_e32 v159, v159
	s_mov_b32 s67, s56
	s_mov_b32 s56, s57
	s_mov_b32 s57, s58
	s_mov_b32 s58, s67
	s_add_u32 s46, s46, 1
	s_waitcnt vmcnt(3) lgkmcnt(0)
	s_barrier
	s_cmp_lg_u64 s[68:69], 0
	s_cbranch_scc0 .Lat_norescO_443
	v_lshl_add_u32 v250, v252, 4, v249
	ds_read_b128 v[0:3], v250 offset:0
	ds_read_b128 v[4:7], v250 offset:32
	ds_read_b128 v[8:11], v250 offset:64
	ds_read_b128 v[12:15], v250 offset:96
	s_nop 7
	s_nop 7
	s_waitcnt lgkmcnt(0)
	v_mul_f32_e32 v32, v32, v0
	v_mul_f32_e32 v33, v33, v1
	v_mul_f32_e32 v34, v34, v2
	v_mul_f32_e32 v35, v35, v3
	v_mul_f32_e32 v36, v36, v4
	v_mul_f32_e32 v37, v37, v5
	v_mul_f32_e32 v38, v38, v6
	v_mul_f32_e32 v39, v39, v7
	v_mul_f32_e32 v40, v40, v8
	v_mul_f32_e32 v41, v41, v9
	v_mul_f32_e32 v42, v42, v10
	v_mul_f32_e32 v43, v43, v11
	v_mul_f32_e32 v44, v44, v12
	v_mul_f32_e32 v45, v45, v13
	v_mul_f32_e32 v46, v46, v14
	v_mul_f32_e32 v47, v47, v15
	v_mul_f32_e32 v48, v48, v0
	v_mul_f32_e32 v49, v49, v1
	v_mul_f32_e32 v50, v50, v2
	v_mul_f32_e32 v51, v51, v3
	v_mul_f32_e32 v52, v52, v4
	v_mul_f32_e32 v53, v53, v5
	v_mul_f32_e32 v54, v54, v6
	v_mul_f32_e32 v55, v55, v7
	v_mul_f32_e32 v56, v56, v8
	v_mul_f32_e32 v57, v57, v9
	v_mul_f32_e32 v58, v58, v10
	v_mul_f32_e32 v59, v59, v11
	v_mul_f32_e32 v60, v60, v12
	v_mul_f32_e32 v61, v61, v13
	v_mul_f32_e32 v62, v62, v14
	v_mul_f32_e32 v63, v63, v15
	v_mul_f32_e32 v64, v64, v0
	v_mul_f32_e32 v65, v65, v1
	v_mul_f32_e32 v66, v66, v2
	v_mul_f32_e32 v67, v67, v3
	v_mul_f32_e32 v68, v68, v4
	v_mul_f32_e32 v69, v69, v5
	v_mul_f32_e32 v70, v70, v6
	v_mul_f32_e32 v71, v71, v7
	v_mul_f32_e32 v72, v72, v8
	v_mul_f32_e32 v73, v73, v9
	v_mul_f32_e32 v74, v74, v10
	v_mul_f32_e32 v75, v75, v11
	v_mul_f32_e32 v76, v76, v12
	v_mul_f32_e32 v77, v77, v13
	v_mul_f32_e32 v78, v78, v14
	v_mul_f32_e32 v79, v79, v15
	v_mul_f32_e32 v80, v80, v0
	v_mul_f32_e32 v81, v81, v1
	v_mul_f32_e32 v82, v82, v2
	v_mul_f32_e32 v83, v83, v3
	v_mul_f32_e32 v84, v84, v4
	v_mul_f32_e32 v85, v85, v5
	v_mul_f32_e32 v86, v86, v6
	v_mul_f32_e32 v87, v87, v7
	v_mul_f32_e32 v88, v88, v8
	v_mul_f32_e32 v89, v89, v9
	v_mul_f32_e32 v90, v90, v10
	v_mul_f32_e32 v91, v91, v11
	v_mul_f32_e32 v92, v92, v12
	v_mul_f32_e32 v93, v93, v13
	v_mul_f32_e32 v94, v94, v14
	v_mul_f32_e32 v95, v95, v15

.Lat_nomask_945:
	v_add_u32_e32 v3, s58, v244
	ds_read_b64_tr_b16 v[200:201], v250 offset:8192
	ds_read_b64_tr_b16 v[202:203], v250 offset:8704
	ds_read_b64_tr_b16 v[204:205], v250 offset:12288
	ds_read_b64_tr_b16 v[206:207], v250 offset:12800
	s_waitcnt lgkmcnt(4)
	v_mfma_f32_32x32x16_bf16 v[32:47], v[176:179], v[192:195], v[32:47]
	v_max3_f32 v2, v96, v97, v112
	v_max3_f32 v4, v98, v99, v113
	v_max3_f32 v2, v2, v114, v115
	ds_read_b128 v[208:211], v3
	ds_read_b128 v[212:215], v3 offset:512
	v_mfma_f32_32x32x16_bf16 v[48:63], v[176:179], v[196:199], v[48:63]
	v_max3_f32 v2, v2, v100, v101
	v_max3_f32 v4, v4, v102, v103
	v_max3_f32 v2, v2, v116, v117
	ds_read_b128 v[216:219], v3 offset:2048
	ds_read_b128 v[220:223], v3 offset:2560
	ds_read_b64_tr_b16 v[192:193], v250 offset:1024
	ds_read_b64_tr_b16 v[194:195], v250 offset:1536
	ds_read_b64_tr_b16 v[196:197], v250 offset:5120
	ds_read_b64_tr_b16 v[198:199], v250 offset:5632
	s_waitcnt lgkmcnt(8)
	v_mfma_f32_32x32x16_bf16 v[64:79], v[176:179], v[200:203], v[64:79]
	v_max3_f32 v4, v4, v118, v119
	v_max3_f32 v2, v2, v104, v105
	v_max3_f32 v4, v4, v106, v107
	ds_read_b128 v[224:227], v3 offset:4096
	v_mfma_f32_32x32x16_bf16 v[80:95], v[176:179], v[204:207], v[80:95]
	v_max3_f32 v2, v2, v120, v121
	v_max3_f32 v4, v4, v122, v123
	v_max3_f32 v2, v2, v108, v109
	ds_read_b128 v[228:231], v3 offset:4608
	ds_read_b64_tr_b16 v[200:201], v250 offset:9216
	ds_read_b64_tr_b16 v[202:203], v250 offset:9728
	ds_read_b64_tr_b16 v[204:205], v250 offset:13312
	ds_read_b64_tr_b16 v[206:207], v250 offset:13824
	s_waitcnt lgkmcnt(6)
	v_mfma_f32_32x32x16_bf16 v[32:47], v[180:183], v[192:195], v[32:47]
	v_max3_f32 v4, v4, v110, v111
	v_max3_f32 v2, v2, v124, v125
	v_max3_f32 v4, v4, v126, v127
	ds_read_b128 v[232:235], v3 offset:6144
	v_mfma_f32_32x32x16_bf16 v[48:63], v[180:183], v[196:199], v[48:63]
	v_max_f32_e32 v2, v2, v4
	v_mov_b32_e32 v4, v2
	s_nop 1
	v_permlane32_swap_b32_e32 v2, v4
	v_max_f32_e32 v2, v2, v4
	ds_read_b128 v[240:243], v3 offset:6656
	v_mov_b32_e32 v5, 0x41400000
	v_cmp_gt_f32_e32 vcc, v2, v5
	s_mov_b64 s[68:69], vcc
	s_cmp_lg_u64 vcc, 0
	s_cbranch_scc0 .Lat_noresc_862
	v_max_f32_e32 v4, 0, v2
	v_add_f32_e32 v248, v248, v4
	v_sub_f32_e32 v96, v96, v4
	v_sub_f32_e32 v97, v97, v4
	v_sub_f32_e32 v98, v98, v4
	v_sub_f32_e32 v99, v99, v4
	v_sub_f32_e32 v100, v100, v4
	v_sub_f32_e32 v101, v101, v4
	v_sub_f32_e32 v102, v102, v4
	v_sub_f32_e32 v103, v103, v4
	v_sub_f32_e32 v104, v104, v4
	v_sub_f32_e32 v105, v105, v4
	v_sub_f32_e32 v106, v106, v4
	v_sub_f32_e32 v107, v107, v4
	v_sub_f32_e32 v108, v108, v4
	v_sub_f32_e32 v109, v109, v4
	v_sub_f32_e32 v110, v110, v4
	v_sub_f32_e32 v111, v111, v4
	v_sub_f32_e32 v112, v112, v4
	v_sub_f32_e32 v113, v113, v4
	v_sub_f32_e32 v114, v114, v4
	v_sub_f32_e32 v115, v115, v4
	v_sub_f32_e32 v116, v116, v4
	v_sub_f32_e32 v117, v117, v4
	v_sub_f32_e32 v118, v118, v4
	v_sub_f32_e32 v119, v119, v4
	v_sub_f32_e32 v120, v120, v4
	v_sub_f32_e32 v121, v121, v4
	v_sub_f32_e32 v122, v122, v4
	v_sub_f32_e32 v123, v123, v4
	v_sub_f32_e32 v124, v124, v4
	v_sub_f32_e32 v125, v125, v4
	v_sub_f32_e32 v126, v126, v4
	v_sub_f32_e32 v127, v127, v4
	v_xor_b32_e32 v5, 0x80000000, v248
	v_mov_b32_e32 v160, v5
	v_mov_b32_e32 v161, v5
	v_mov_b32_e32 v162, v5
	v_mov_b32_e32 v163, v5
	v_mov_b32_e32 v164, v5
	v_mov_b32_e32 v165, v5
	v_mov_b32_e32 v166, v5
	v_mov_b32_e32 v167, v5
	v_mov_b32_e32 v168, v5
	v_mov_b32_e32 v169, v5
	v_mov_b32_e32 v170, v5
	v_mov_b32_e32 v171, v5
	v_mov_b32_e32 v172, v5
	v_mov_b32_e32 v173, v5
	v_mov_b32_e32 v174, v5
	v_mov_b32_e32 v175, v5
	v_xor_b32_e32 v6, 0x80000000, v4
	v_exp_f32_e32 v6, v6
	s_nop 0
	v_mul_f32_e32 v247, v247, v6
	v_and_b32_e32 v7, 31, v237
	v_lshl_add_u32 v7, v7, 2, v249
	v_cmp_eq_u32_e32 vcc, 0, v252
	s_and_saveexec_b64 s[60:61], vcc
	ds_write_b32 v7, v6
	s_or_b64 exec, exec, s[60:61]
.Lat_noresc_862:
	ds_read_b64_tr_b16 v[192:193], v250 offset:2048
	ds_read_b64_tr_b16 v[194:195], v250 offset:2560
	ds_read_b64_tr_b16 v[196:197], v250 offset:6144
	ds_read_b64_tr_b16 v[198:199], v250 offset:6656
	s_waitcnt lgkmcnt(6)
	v_mfma_f32_32x32x16_bf16 v[64:79], v[180:183], v[200:203], v[64:79]
	v_exp_f32_e32 v96, v96
	v_exp_f32_e32 v97, v97
	v_exp_f32_e32 v98, v98
	v_mfma_f32_32x32x16_bf16 v[80:95], v[180:183], v[204:207], v[80:95]
	v_exp_f32_e32 v99, v99
	v_exp_f32_e32 v100, v100
	v_exp_f32_e32 v101, v101
	ds_read_b64_tr_b16 v[200:201], v250 offset:10240
	ds_read_b64_tr_b16 v[202:203], v250 offset:10752
	ds_read_b64_tr_b16 v[204:205], v250 offset:14336
	ds_read_b64_tr_b16 v[206:207], v250 offset:14848
	s_waitcnt lgkmcnt(4)
	v_mfma_f32_32x32x16_bf16 v[32:47], v[184:187], v[192:195], v[32:47]
	v_exp_f32_e32 v102, v102
	v_exp_f32_e32 v103, v103
	v_exp_f32_e32 v104, v104
	v_mfma_f32_32x32x16_bf16 v[48:63], v[184:187], v[196:199], v[48:63]
	v_exp_f32_e32 v105, v105
	v_exp_f32_e32 v106, v106
	v_exp_f32_e32 v107, v107
	ds_read_b64_tr_b16 v[192:193], v250 offset:3072
	ds_read_b64_tr_b16 v[194:195], v250 offset:3584
	ds_read_b64_tr_b16 v[196:197], v250 offset:7168
	ds_read_b64_tr_b16 v[198:199], v250 offset:7680
	s_waitcnt lgkmcnt(4)
	v_mfma_f32_32x32x16_bf16 v[64:79], v[184:187], v[200:203], v[64:79]
	v_exp_f32_e32 v108, v108
	v_exp_f32_e32 v109, v109
	v_exp_f32_e32 v110, v110
	v_mfma_f32_32x32x16_bf16 v[80:95], v[184:187], v[204:207], v[80:95]
	v_exp_f32_e32 v111, v111
	v_exp_f32_e32 v112, v112
	v_exp_f32_e32 v113, v113
	ds_read_b64_tr_b16 v[200:201], v250 offset:11264
	ds_read_b64_tr_b16 v[202:203], v250 offset:11776
	ds_read_b64_tr_b16 v[204:205], v250 offset:15360
	ds_read_b64_tr_b16 v[206:207], v250 offset:15872
	s_waitcnt lgkmcnt(4)
	v_mfma_f32_32x32x16_bf16 v[32:47], v[188:191], v[192:195], v[32:47]
	v_exp_f32_e32 v114, v114
	v_exp_f32_e32 v115, v115
	v_exp_f32_e32 v116, v116
	v_mfma_f32_32x32x16_bf16 v[48:63], v[188:191], v[196:199], v[48:63]
	v_exp_f32_e32 v117, v117
	v_exp_f32_e32 v118, v118
	v_exp_f32_e32 v119, v119
	s_waitcnt lgkmcnt(0)
	v_mfma_f32_32x32x16_bf16 v[64:79], v[188:191], v[200:203], v[64:79]
	v_exp_f32_e32 v120, v120
	v_exp_f32_e32 v121, v121
	v_exp_f32_e32 v122, v122
	v_exp_f32_e32 v123, v123
	v_mfma_f32_32x32x16_bf16 v[80:95], v[188:191], v[204:207], v[80:95]
	v_exp_f32_e32 v124, v124
	v_exp_f32_e32 v125, v125
	v_exp_f32_e32 v126, v126
	v_exp_f32_e32 v127, v127
	s_mov_b32 s67, s56
	s_mov_b32 s56, s57
	s_mov_b32 s57, s58
	s_mov_b32 s58, s67
	s_add_u32 s46, s46, 1
	s_waitcnt vmcnt(3) lgkmcnt(0)
	s_barrier
	s_cmp_lg_u64 s[68:69], 0
	s_cbranch_scc0 .Lat_norescO_862
	v_lshl_add_u32 v250, v252, 4, v249
	ds_read_b128 v[0:3], v250 offset:0
	ds_read_b128 v[4:7], v250 offset:32
	ds_read_b128 v[8:11], v250 offset:64
	ds_read_b128 v[12:15], v250 offset:96
	s_nop 7
	s_nop 7
	s_waitcnt lgkmcnt(0)
	v_mul_f32_e32 v32, v32, v0
	v_mul_f32_e32 v33, v33, v1
	v_mul_f32_e32 v34, v34, v2
	v_mul_f32_e32 v35, v35, v3
	v_mul_f32_e32 v36, v36, v4
	v_mul_f32_e32 v37, v37, v5
	v_mul_f32_e32 v38, v38, v6
	v_mul_f32_e32 v39, v39, v7
	v_mul_f32_e32 v40, v40, v8
	v_mul_f32_e32 v41, v41, v9
	v_mul_f32_e32 v42, v42, v10
	v_mul_f32_e32 v43, v43, v11
	v_mul_f32_e32 v44, v44, v12
	v_mul_f32_e32 v45, v45, v13
	v_mul_f32_e32 v46, v46, v14
	v_mul_f32_e32 v47, v47, v15
	v_mul_f32_e32 v48, v48, v0
	v_mul_f32_e32 v49, v49, v1
	v_mul_f32_e32 v50, v50, v2
	v_mul_f32_e32 v51, v51, v3
	v_mul_f32_e32 v52, v52, v4
	v_mul_f32_e32 v53, v53, v5
	v_mul_f32_e32 v54, v54, v6
	v_mul_f32_e32 v55, v55, v7
	v_mul_f32_e32 v56, v56, v8
	v_mul_f32_e32 v57, v57, v9
	v_mul_f32_e32 v58, v58, v10
	v_mul_f32_e32 v59, v59, v11
	v_mul_f32_e32 v60, v60, v12
	v_mul_f32_e32 v61, v61, v13
	v_mul_f32_e32 v62, v62, v14
	v_mul_f32_e32 v63, v63, v15
	v_mul_f32_e32 v64, v64, v0
	v_mul_f32_e32 v65, v65, v1
	v_mul_f32_e32 v66, v66, v2
	v_mul_f32_e32 v67, v67, v3
	v_mul_f32_e32 v68, v68, v4
	v_mul_f32_e32 v69, v69, v5
	v_mul_f32_e32 v70, v70, v6
	v_mul_f32_e32 v71, v71, v7
	v_mul_f32_e32 v72, v72, v8
	v_mul_f32_e32 v73, v73, v9
	v_mul_f32_e32 v74, v74, v10
	v_mul_f32_e32 v75, v75, v11
	v_mul_f32_e32 v76, v76, v12
	v_mul_f32_e32 v77, v77, v13
	v_mul_f32_e32 v78, v78, v14
	v_mul_f32_e32 v79, v79, v15
	v_mul_f32_e32 v80, v80, v0
	v_mul_f32_e32 v81, v81, v1
	v_mul_f32_e32 v82, v82, v2
	v_mul_f32_e32 v83, v83, v3
	v_mul_f32_e32 v84, v84, v4
	v_mul_f32_e32 v85, v85, v5
	v_mul_f32_e32 v86, v86, v6
	v_mul_f32_e32 v87, v87, v7
	v_mul_f32_e32 v88, v88, v8
	v_mul_f32_e32 v89, v89, v9
	v_mul_f32_e32 v90, v90, v10
	v_mul_f32_e32 v91, v91, v11
	v_mul_f32_e32 v92, v92, v12
	v_mul_f32_e32 v93, v93, v13
	v_mul_f32_e32 v94, v94, v14
	v_mul_f32_e32 v95, v95, v15
